# stacked: scan rounds 132->129, dead logf guards removed in attention softplus, attention output staged through LDS (256 B rows)
# baseline (speedup 1.0000x reference)
; DI unsigned cvt_pk_bf16(float lo, float hi) { const f32x2 v = {lo, hi}; const bf16x2_t b = __builtin_convertvector(v, bf16x2_t); return __builtin_bit_cast(unsigned, b); }
; template <bool SAMP> DI void attn_wave_unit(const Params& p, int u, int lane_) {
;     ...
;     bf16_t* op = AO + (orow0 + r32) * 1024 + h * 128 + 4 * hh;
; #pragma unroll
;     for (int d = 0; d < 4; ++d)
; #pragma unroll
;         for (int g = 0; g < 4; ++g) { u32x2 t; t.x = cvt_pk_bf16(oacc[d][4 * g], oacc[d][4 * g + 1]); t.y = cvt_pk_bf16(oacc[d][4 * g + 2], oacc[d][4 * g + 3]);
;             *(u32x2*)(op + 32 * d + 8 * g) = t; }
.LBB0_178:
	s_waitcnt vmcnt(0)
	v_lshlrev_b32_e32 v180, 11, v64
	v_lshl_add_u64 v[64:65], s[78:79], 0, v[180:181]
	v_lshlrev_b32_e32 v66, 2, v213
	v_lshl_add_u64 v[64:65], s[4:5], 1, v[64:65]
	v_ashrrev_i32_e32 v67, 31, v66
	v_lshl_add_u64 v[64:65], v[66:67], 1, v[64:65]
	v_and_b32_e32 v68, 63, v202
	v_lshrrev_b32_e32 v69, 6, v202
	v_and_b32_e32 v70, 31, v68
	v_lshrrev_b32_e32 v71, 5, v68
	v_mul_u32_u24_e32 v69, 0x2200, v69
	v_mul_u32_u24_e32 v72, 0x110, v70
	v_add_u32_e32 v72, v72, v69
	v_lshl_add_u32 v72, v71, 3, v72
	v_lshrrev_b32_e32 v73, 4, v68
	v_and_b32_e32 v74, 15, v68
	v_mul_u32_u24_e32 v75, 0x110, v73
	v_add_u32_e32 v75, v75, v69
	v_lshl_add_u32 v75, v74, 4, v75
	v_sub_u32_e32 v76, v73, v70
	v_lshlrev_b32_e32 v76, 11, v76
	v_lshl_add_u32 v76, v74, 4, v76
	v_lshlrev_b32_e32 v77, 3, v71
	v_sub_u32_e32 v66, v76, v77
	v_ashrrev_i32_e32 v67, 31, v66
	v_lshl_add_u64 v[64:65], v[64:65], 0, v[66:67]
	s_mov_b64 s[98:99], 0x2000
	v_cvt_pk_bf16_f32 v0, v0, v1
	v_cvt_pk_bf16_f32 v1, v2, v3
	ds_write_b64 v72, v[0:1]
	v_cvt_pk_bf16_f32 v4, v4, v5
	v_cvt_pk_bf16_f32 v5, v6, v7
	ds_write_b64 v72, v[4:5] offset:16
	v_cvt_pk_bf16_f32 v8, v8, v9
	v_cvt_pk_bf16_f32 v9, v10, v11
	ds_write_b64 v72, v[8:9] offset:32
	v_cvt_pk_bf16_f32 v12, v12, v13
	v_cvt_pk_bf16_f32 v13, v14, v15
	ds_write_b64 v72, v[12:13] offset:48
	v_cvt_pk_bf16_f32 v16, v16, v17
	v_cvt_pk_bf16_f32 v17, v18, v19
	ds_write_b64 v72, v[16:17] offset:64
	v_cvt_pk_bf16_f32 v20, v20, v21
	v_cvt_pk_bf16_f32 v21, v22, v23
	ds_write_b64 v72, v[20:21] offset:80
	v_cvt_pk_bf16_f32 v24, v24, v25
	v_cvt_pk_bf16_f32 v25, v26, v27
	ds_write_b64 v72, v[24:25] offset:96
	v_cvt_pk_bf16_f32 v28, v28, v29
	v_cvt_pk_bf16_f32 v29, v30, v31
	ds_write_b64 v72, v[28:29] offset:112
	v_cvt_pk_bf16_f32 v32, v32, v33
	v_cvt_pk_bf16_f32 v33, v34, v35
	ds_write_b64 v72, v[32:33] offset:128
	v_cvt_pk_bf16_f32 v36, v36, v37
	v_cvt_pk_bf16_f32 v37, v38, v39
	ds_write_b64 v72, v[36:37] offset:144
	v_cvt_pk_bf16_f32 v40, v40, v41
	v_cvt_pk_bf16_f32 v41, v42, v43
	ds_write_b64 v72, v[40:41] offset:160
	v_cvt_pk_bf16_f32 v44, v44, v45
	v_cvt_pk_bf16_f32 v45, v46, v47
	ds_write_b64 v72, v[44:45] offset:176
	v_cvt_pk_bf16_f32 v48, v48, v49
	v_cvt_pk_bf16_f32 v49, v50, v51
	ds_write_b64 v72, v[48:49] offset:192
	v_cvt_pk_bf16_f32 v52, v52, v53
	v_cvt_pk_bf16_f32 v53, v54, v55
	ds_write_b64 v72, v[52:53] offset:208
	v_cvt_pk_bf16_f32 v56, v56, v57
	v_cvt_pk_bf16_f32 v57, v58, v59
	ds_write_b64 v72, v[56:57] offset:224
	v_cvt_pk_bf16_f32 v60, v60, v61
	v_cvt_pk_bf16_f32 v61, v62, v63
	ds_write_b64 v72, v[60:61] offset:240
	ds_read_b128 v[0:3], v75
	ds_read_b128 v[4:7], v75 offset:1088
	ds_read_b128 v[8:11], v75 offset:2176
	ds_read_b128 v[12:15], v75 offset:3264
	ds_read_b128 v[16:19], v75 offset:4352
	ds_read_b128 v[20:23], v75 offset:5440
	ds_read_b128 v[24:27], v75 offset:6528
	ds_read_b128 v[28:31], v75 offset:7616
	s_waitcnt lgkmcnt(7)
	global_store_dwordx4 v[64:65], v[0:3], off
	s_waitcnt lgkmcnt(6)
	v_lshl_add_u64 v[64:65], v[64:65], 0, s[98:99]
	global_store_dwordx4 v[64:65], v[4:7], off
	s_waitcnt lgkmcnt(5)
	v_lshl_add_u64 v[64:65], v[64:65], 0, s[98:99]
	global_store_dwordx4 v[64:65], v[8:11], off
	s_waitcnt lgkmcnt(4)
	v_lshl_add_u64 v[64:65], v[64:65], 0, s[98:99]
	global_store_dwordx4 v[64:65], v[12:15], off
	s_waitcnt lgkmcnt(3)
	v_lshl_add_u64 v[64:65], v[64:65], 0, s[98:99]
	global_store_dwordx4 v[64:65], v[16:19], off
	s_waitcnt lgkmcnt(2)
	v_lshl_add_u64 v[64:65], v[64:65], 0, s[98:99]
	global_store_dwordx4 v[64:65], v[20:23], off
	s_waitcnt lgkmcnt(1)
	v_lshl_add_u64 v[64:65], v[64:65], 0, s[98:99]
	global_store_dwordx4 v[64:65], v[24:27], off
	s_waitcnt lgkmcnt(0)
	v_lshl_add_u64 v[64:65], v[64:65], 0, s[98:99]
	global_store_dwordx4 v[64:65], v[28:31], off
	s_mov_b64 s[0:1], 0

; DI unsigned cvt_pk_bf16(float lo, float hi) { const f32x2 v = {lo, hi}; const bf16x2_t b = __builtin_convertvector(v, bf16x2_t); return __builtin_bit_cast(unsigned, b); }
; #define MFMA32(a, b, c) __builtin_amdgcn_mfma_f32_32x32x16_bf16((a), (b), (c), 0, 0, 0)
; template <bool SAMP> DI void attn_wave_unit(const Params& p, int u, int lane_) {
;     ...
;         f32x16 st;
; #pragma unroll
;         for (int i = 0; i < 16; ++i) st[i] = 0.f;
; #pragma unroll
;         for (int s = 0; s < 8; ++s) st = MFMA32(kf[s], qf[s], st);
;         bf16x8 vf[8];
;         if (SAMP && kt < 32) {
;             const float* vcp = vc + (size_t)(kt * 32 + 16 * hh) * 128 + r32;
; #pragma unroll
;             for (int d = 0; d < 4; ++d) {
;                 float t[16];
; #pragma unroll
;                 for (int j = 0; j < 16; ++j) t[j] = vcp[(size_t)j * 128 + 32 * d];
;                 u32x4 a, b2;
;                 a.x = cvt_pk_bf16(t[0], t[1]); a.y = cvt_pk_bf16(t[2], t[3]); a.z = cvt_pk_bf16(t[4], t[5]); a.w = cvt_pk_bf16(t[6], t[7]);
;                 b2.x = cvt_pk_bf16(t[8], t[9]); b2.y = cvt_pk_bf16(t[10], t[11]); b2.z = cvt_pk_bf16(t[12], t[13]); b2.w = cvt_pk_bf16(t[14], t[15]);
;                 vf[2 * d] = __builtin_bit_cast(bf16x8, a); vf[2 * d + 1] = __builtin_bit_cast(bf16x8, b2);
;                 __builtin_amdgcn_sched_barrier(0);
;             }
;         } else {
; #pragma unroll
;             for (int d = 0; d < 4; ++d) { const bf16_t* vr = Vt + ((size_t)kt * 4 + d) * 1024 + lane * 8;
;                 vf[2 * d] = *(const bf16x8*)vr; vf[2 * d + 1] = *(const bf16x8*)(vr + 512); }
;         }
;         __builtin_amdgcn_sched_barrier(0);
;         loadK(kt > 0 ? kt - 1 : 0, kf);
;         __builtin_amdgcn_sched_barrier(0);
;         float lr[16], zz[16];
;         const int kbase = kt * 32 + 16 * hh;
;         float tot = 0.f;
; #pragma unroll
;         for (int i = 0; i < 16; ++i) { const float z = st[i] * scale;
;             const float sp = fmaxf(z, 0.f) + __logf(1.f + __expf(-fabsf(z)));
;             const bool valid = (kbase + i) < qpos; lr[i] = valid ? -sp : 0.f; zz[i] = valid ? (z - sp) : -1e30f; tot += lr[i]; }
.LBB0_187:
	s_waitcnt vmcnt(7)
	v_mfma_f32_32x32x16_bf16 v[64:79], v[124:127], v[80:83], 0
	v_lshl_add_u64 v[124:125], v[178:179], 0, s[92:93]
	s_mov_b32 s0, 0x5200000
	v_add_co_u32_e32 v126, vcc, s0, v124
	s_mov_b32 s0, 0x5201000
	s_nop 0
	v_addc_co_u32_e32 v127, vcc, 0, v125, vcc
	s_waitcnt vmcnt(6)
	v_mfma_f32_32x32x16_bf16 v[64:79], v[128:131], v[84:87], v[64:79]
	s_waitcnt vmcnt(5)
	v_mfma_f32_32x32x16_bf16 v[64:79], v[132:135], v[88:91], v[64:79]
	s_waitcnt vmcnt(4)
	v_mfma_f32_32x32x16_bf16 v[64:79], v[136:139], v[92:95], v[64:79]
	s_waitcnt vmcnt(3)
	v_mfma_f32_32x32x16_bf16 v[64:79], v[140:143], v[96:99], v[64:79]
	s_waitcnt vmcnt(2)
	v_mfma_f32_32x32x16_bf16 v[64:79], v[120:123], v[100:103], v[64:79]
	v_add_co_u32_e32 v120, vcc, s0, v124
	s_min_u32 s0, s20, 1
	s_nop 0
	v_addc_co_u32_e32 v121, vcc, 0, v125, vcc
	global_load_dwordx4 v[168:171], v[126:127], off offset:1024
	global_load_dwordx4 v[160:163], v[126:127], off offset:2048
	global_load_dwordx4 v[172:175], v[120:121], off offset:-4096
	global_load_dwordx4 v[164:167], v[126:127], off offset:3072
	global_load_dwordx4 v[152:155], v[120:121], off
	global_load_dwordx4 v[156:159], v[120:121], off offset:1024
	global_load_dwordx4 v[144:147], v[120:121], off offset:2048
	global_load_dwordx4 v[148:151], v[120:121], off offset:3072
	s_waitcnt vmcnt(9)
	v_mfma_f32_32x32x16_bf16 v[64:79], v[116:119], v[104:107], v[64:79]
	s_lshl_b32 s0, s0, 5
	v_subrev_u32_e32 v116, s0, v189
	s_waitcnt vmcnt(8)
	v_mfma_f32_32x32x16_bf16 v[64:79], v[112:115], v[108:111], v[64:79]
	v_add_u32_e32 v112, s21, v116
	v_mad_u64_u32 v[112:113], s[0:1], v112, s91, v[176:177]
	global_load_dwordx4 v[124:127], v[112:113], off offset:2048
	global_load_dwordx4 v[128:131], v[112:113], off offset:2080
	global_load_dwordx4 v[132:135], v[112:113], off offset:2112
	global_load_dwordx4 v[136:139], v[112:113], off offset:2144
	global_load_dwordx4 v[140:143], v[112:113], off offset:2176
	global_load_dwordx4 v[120:123], v[112:113], off offset:2208
	global_load_dwordx4 v[116:119], v[112:113], off offset:2240
	s_nop 0
	global_load_dwordx4 v[112:115], v[112:113], off offset:2272
	s_nop 0
	v_mul_f32_e32 v215, 0x3db504f3, v64
	v_max_f32_e32 v216, 0, v215
	v_mul_f32_e64 v215, |v215|, s71
	v_exp_f32_e32 v215, v215
	v_add_u32_e32 v226, s21, v188
	v_lshl_add_u64 v[178:179], v[178:179], 0, s[94:95]
	v_add_f32_e32 v215, 1.0, v215
	v_log_f32_e32 v215, v215
	s_nop 0
	v_mul_f32_e32 v217, 0x3f317217, v215
	v_fma_f32 v217, v215, s8, -v217
	v_fmac_f32_e32 v217, 0x3377d1cf, v215
	v_fmac_f32_e32 v217, 0x3f317217, v215
	v_mov_b32_e32 v215, v217
	v_add_f32_e32 v215, v216, v215
	v_cmp_lt_i32_e32 vcc, v226, v183
	v_fma_f32 v64, v64, s70, -v215
	v_sub_f32_e32 v215, 0, v215
	v_cndmask_b32_e32 v216, 0, v215, vcc
	v_mul_f32_e32 v215, 0x3db504f3, v65
	v_max_f32_e32 v217, 0, v215
	v_mul_f32_e64 v215, |v215|, s71
	v_exp_f32_e32 v215, v215
	v_cndmask_b32_e32 v64, v199, v64, vcc
	v_add_f32_e32 v215, 1.0, v215
	v_log_f32_e32 v215, v215
	s_nop 0
	v_mul_f32_e32 v218, 0x3f317217, v215
	v_fma_f32 v218, v215, s8, -v218
	v_fmac_f32_e32 v218, 0x3377d1cf, v215
	v_fmac_f32_e32 v218, 0x3f317217, v215
	v_mov_b32_e32 v215, v218
	v_add_f32_e32 v217, v217, v215
	v_add_u32_e32 v215, 1, v226
	v_cmp_lt_i32_e32 vcc, v215, v183
	v_fma_f32 v65, v65, s70, -v217
	s_nop 0
	v_cndmask_b32_e64 v215, 0, -v217, vcc
	v_add_f32_e32 v217, v215, v216
	v_mul_f32_e32 v216, 0x3db504f3, v66
	v_max_f32_e32 v218, 0, v216
	v_mul_f32_e64 v216, |v216|, s71
	v_exp_f32_e32 v216, v216
	v_cndmask_b32_e32 v65, v199, v65, vcc
	v_add_f32_e32 v216, 1.0, v216
	v_log_f32_e32 v216, v216
	s_nop 0
	v_mul_f32_e32 v219, 0x3f317217, v216
	v_fma_f32 v219, v216, s8, -v219
	v_fmac_f32_e32 v219, 0x3377d1cf, v216
	v_fmac_f32_e32 v219, 0x3f317217, v216
	v_mov_b32_e32 v216, v219
	v_add_f32_e32 v218, v218, v216
	v_add_u32_e32 v216, 2, v226
	v_cmp_lt_i32_e32 vcc, v216, v183
	v_fma_f32 v66, v66, s70, -v218
	s_nop 0
	v_cndmask_b32_e64 v216, 0, -v218, vcc
	v_add_f32_e32 v218, v216, v217
	v_mul_f32_e32 v217, 0x3db504f3, v67
	v_max_f32_e32 v219, 0, v217
	v_mul_f32_e64 v217, |v217|, s71
	v_exp_f32_e32 v217, v217
	v_cndmask_b32_e32 v66, v199, v66, vcc
	v_add_f32_e32 v217, 1.0, v217
	v_log_f32_e32 v217, v217
	s_nop 0
	v_mul_f32_e32 v220, 0x3f317217, v217
	v_fma_f32 v220, v217, s8, -v220
	v_fmac_f32_e32 v220, 0x3377d1cf, v217
	v_fmac_f32_e32 v220, 0x3f317217, v217
	v_mov_b32_e32 v217, v220
	v_add_f32_e32 v219, v219, v217
	v_add_u32_e32 v217, 3, v226
	v_cmp_lt_i32_e32 vcc, v217, v183
	v_fma_f32 v67, v67, s70, -v219
	s_nop 0
	v_cndmask_b32_e64 v217, 0, -v219, vcc
	v_add_f32_e32 v219, v217, v218
	v_mul_f32_e32 v218, 0x3db504f3, v68
	v_max_f32_e32 v220, 0, v218
	v_mul_f32_e64 v218, |v218|, s71
	v_exp_f32_e32 v218, v218
	v_cndmask_b32_e32 v67, v199, v67, vcc
	v_add_f32_e32 v218, 1.0, v218
	v_log_f32_e32 v218, v218
	s_nop 0
	v_mul_f32_e32 v221, 0x3f317217, v218
	v_fma_f32 v221, v218, s8, -v221
	v_fmac_f32_e32 v221, 0x3377d1cf, v218
	v_fmac_f32_e32 v221, 0x3f317217, v218
	v_mov_b32_e32 v218, v221
	v_add_f32_e32 v220, v220, v218
	v_add_u32_e32 v218, 4, v226
	v_cmp_lt_i32_e32 vcc, v218, v183
	v_fma_f32 v68, v68, s70, -v220
	s_nop 0
	v_cndmask_b32_e64 v218, 0, -v220, vcc
	v_add_f32_e32 v220, v218, v219
	v_mul_f32_e32 v219, 0x3db504f3, v69
	v_max_f32_e32 v221, 0, v219
	v_mul_f32_e64 v219, |v219|, s71
	v_exp_f32_e32 v219, v219
	v_cndmask_b32_e32 v68, v199, v68, vcc
	v_add_f32_e32 v219, 1.0, v219
	v_log_f32_e32 v219, v219
	s_nop 0
	v_mul_f32_e32 v222, 0x3f317217, v219
	v_fma_f32 v222, v219, s8, -v222
	v_fmac_f32_e32 v222, 0x3377d1cf, v219
	v_fmac_f32_e32 v222, 0x3f317217, v219
	v_mov_b32_e32 v219, v222
	v_add_f32_e32 v221, v221, v219
; template <bool SAMP> DI void attn_wave_unit(const Params& p, int u, int lane_) {
;     ...
;         const int kbase = kt * 32 + 16 * hh;
;         float tot = 0.f;
; #pragma unroll
;         for (int i = 0; i < 16; ++i) { const float z = st[i] * scale;
;             const float sp = fmaxf(z, 0.f) + __logf(1.f + __expf(-fabsf(z)));
;             const bool valid = (kbase + i) < qpos; lr[i] = valid ? -sp : 0.f; zz[i] = valid ? (z - sp) : -1e30f; tot += lr[i]; }
	v_add_u32_e32 v219, 5, v226
	v_cmp_lt_i32_e32 vcc, v219, v183
	v_fma_f32 v69, v69, s70, -v221
	s_nop 0
	v_cndmask_b32_e64 v219, 0, -v221, vcc
	v_add_f32_e32 v221, v219, v220
	v_mul_f32_e32 v220, 0x3db504f3, v70
	v_max_f32_e32 v222, 0, v220
	v_mul_f32_e64 v220, |v220|, s71
	v_exp_f32_e32 v220, v220
	v_cndmask_b32_e32 v69, v199, v69, vcc
	v_add_f32_e32 v220, 1.0, v220
	v_log_f32_e32 v220, v220
	s_nop 0
	v_mul_f32_e32 v223, 0x3f317217, v220
	v_fma_f32 v223, v220, s8, -v223
	v_fmac_f32_e32 v223, 0x3377d1cf, v220
	v_fmac_f32_e32 v223, 0x3f317217, v220
	v_mov_b32_e32 v220, v223
	v_add_f32_e32 v222, v222, v220
	v_add_u32_e32 v220, 6, v226
	v_cmp_lt_i32_e32 vcc, v220, v183
	v_fma_f32 v70, v70, s70, -v222
	s_nop 0
	v_cndmask_b32_e64 v220, 0, -v222, vcc
	v_add_f32_e32 v222, v220, v221
	v_mul_f32_e32 v221, 0x3db504f3, v71
	v_max_f32_e32 v223, 0, v221
	v_mul_f32_e64 v221, |v221|, s71
	v_exp_f32_e32 v221, v221
	v_cndmask_b32_e32 v70, v199, v70, vcc
	v_add_f32_e32 v221, 1.0, v221
	v_log_f32_e32 v221, v221
	s_nop 0
	v_mul_f32_e32 v224, 0x3f317217, v221
	v_fma_f32 v224, v221, s8, -v224
	v_fmac_f32_e32 v224, 0x3377d1cf, v221
	v_fmac_f32_e32 v224, 0x3f317217, v221
	v_mov_b32_e32 v221, v224
	v_add_f32_e32 v223, v223, v221
	v_add_u32_e32 v221, 7, v226
	v_cmp_lt_i32_e32 vcc, v221, v183
	v_fma_f32 v71, v71, s70, -v223
	s_nop 0
	v_cndmask_b32_e64 v221, 0, -v223, vcc
	v_add_f32_e32 v223, v221, v222
	v_mul_f32_e32 v222, 0x3db504f3, v72
	v_max_f32_e32 v224, 0, v222
	v_mul_f32_e64 v222, |v222|, s71
	v_exp_f32_e32 v222, v222
	v_cndmask_b32_e32 v71, v199, v71, vcc
	v_add_f32_e32 v222, 1.0, v222
	v_log_f32_e32 v222, v222
	s_nop 0
	v_mul_f32_e32 v225, 0x3f317217, v222
	v_fma_f32 v225, v222, s8, -v225
	v_fmac_f32_e32 v225, 0x3377d1cf, v222
	v_fmac_f32_e32 v225, 0x3f317217, v222
	v_mov_b32_e32 v222, v225
	v_add_f32_e32 v224, v224, v222
	v_add_u32_e32 v222, 8, v226
	v_cmp_lt_i32_e32 vcc, v222, v183
	v_fma_f32 v72, v72, s70, -v224
	s_nop 0
	v_cndmask_b32_e64 v222, 0, -v224, vcc
	v_add_f32_e32 v224, v222, v223
	v_mul_f32_e32 v223, 0x3db504f3, v73
	v_max_f32_e32 v225, 0, v223
	v_mul_f32_e64 v223, |v223|, s71
	v_exp_f32_e32 v223, v223
	v_cndmask_b32_e32 v72, v199, v72, vcc
	v_add_f32_e32 v223, 1.0, v223
	v_log_f32_e32 v223, v223
	s_nop 0
	v_mul_f32_e32 v227, 0x3f317217, v223
	v_fma_f32 v227, v223, s8, -v227
	v_fmac_f32_e32 v227, 0x3377d1cf, v223
	v_fmac_f32_e32 v227, 0x3f317217, v223
	v_mov_b32_e32 v223, v227
	v_add_f32_e32 v225, v225, v223
	v_add_u32_e32 v223, 9, v226
	v_cmp_lt_i32_e32 vcc, v223, v183
	v_fma_f32 v73, v73, s70, -v225
	s_nop 0
	v_cndmask_b32_e64 v223, 0, -v225, vcc
	v_add_f32_e32 v225, v223, v224
	v_mul_f32_e32 v224, 0x3db504f3, v74
	v_max_f32_e32 v227, 0, v224
	v_mul_f32_e64 v224, |v224|, s71
	v_exp_f32_e32 v224, v224
	v_cndmask_b32_e32 v73, v199, v73, vcc
	v_add_f32_e32 v224, 1.0, v224
	v_log_f32_e32 v224, v224
	s_nop 0
	v_mul_f32_e32 v228, 0x3f317217, v224
	v_fma_f32 v228, v224, s8, -v228
	v_fmac_f32_e32 v228, 0x3377d1cf, v224
	v_fmac_f32_e32 v228, 0x3f317217, v224
	v_mov_b32_e32 v224, v228
	v_add_f32_e32 v227, v227, v224
	v_add_u32_e32 v224, 10, v226
	v_cmp_lt_i32_e32 vcc, v224, v183
	v_fma_f32 v74, v74, s70, -v227
	s_nop 0
	v_cndmask_b32_e64 v224, 0, -v227, vcc
	v_add_f32_e32 v227, v224, v225
	v_mul_f32_e32 v225, 0x3db504f3, v75
	v_max_f32_e32 v228, 0, v225
	v_mul_f32_e64 v225, |v225|, s71
	v_exp_f32_e32 v225, v225
	v_cndmask_b32_e32 v74, v199, v74, vcc
	v_add_f32_e32 v225, 1.0, v225
	v_log_f32_e32 v225, v225
	s_nop 0
	v_mul_f32_e32 v229, 0x3f317217, v225
	v_fma_f32 v229, v225, s8, -v229
	v_fmac_f32_e32 v229, 0x3377d1cf, v225
	v_fmac_f32_e32 v229, 0x3f317217, v225
	v_mov_b32_e32 v225, v229
	v_add_f32_e32 v228, v228, v225
	v_add_u32_e32 v225, 11, v226
	v_cmp_lt_i32_e32 vcc, v225, v183
	v_fma_f32 v75, v75, s70, -v228
	s_nop 0
	v_cndmask_b32_e64 v225, 0, -v228, vcc
	v_add_f32_e32 v228, v225, v227
	v_mul_f32_e32 v227, 0x3db504f3, v76
	v_max_f32_e32 v229, 0, v227
	v_mul_f32_e64 v227, |v227|, s71
	v_exp_f32_e32 v227, v227
	v_cndmask_b32_e32 v75, v199, v75, vcc
	v_add_f32_e32 v227, 1.0, v227
	v_log_f32_e32 v227, v227
	s_nop 0
	v_mul_f32_e32 v230, 0x3f317217, v227
	v_fma_f32 v230, v227, s8, -v230
	v_fmac_f32_e32 v230, 0x3377d1cf, v227
	v_fmac_f32_e32 v230, 0x3f317217, v227
	v_mov_b32_e32 v227, v230
	v_add_f32_e32 v229, v229, v227
	v_add_u32_e32 v227, 12, v226
	v_cmp_lt_i32_e32 vcc, v227, v183
	v_fma_f32 v76, v76, s70, -v229
	s_nop 0
	v_cndmask_b32_e64 v227, 0, -v229, vcc
	v_add_f32_e32 v229, v227, v228
	v_mul_f32_e32 v228, 0x3db504f3, v77
	v_max_f32_e32 v230, 0, v228
	v_mul_f32_e64 v228, |v228|, s71
	v_exp_f32_e32 v228, v228
	v_cndmask_b32_e32 v76, v199, v76, vcc
	v_add_f32_e32 v228, 1.0, v228
	v_log_f32_e32 v228, v228
	s_nop 0
	v_mul_f32_e32 v231, 0x3f317217, v228
	v_fma_f32 v231, v228, s8, -v231
	v_fmac_f32_e32 v231, 0x3377d1cf, v228
	v_fmac_f32_e32 v231, 0x3f317217, v228
	v_mov_b32_e32 v228, v231
	v_add_f32_e32 v230, v230, v228
	v_add_u32_e32 v228, 13, v226
	v_cmp_lt_i32_e32 vcc, v228, v183
	v_fma_f32 v77, v77, s70, -v230
	s_nop 0
	v_cndmask_b32_e64 v228, 0, -v230, vcc
	v_add_f32_e32 v230, v228, v229
	v_mul_f32_e32 v229, 0x3db504f3, v78
	v_max_f32_e32 v231, 0, v229
	v_mul_f32_e64 v229, |v229|, s71
	v_exp_f32_e32 v229, v229
	v_cndmask_b32_e32 v77, v199, v77, vcc
	v_add_f32_e32 v229, 1.0, v229
	v_log_f32_e32 v229, v229
	s_nop 0
	v_mul_f32_e32 v232, 0x3f317217, v229
	v_fma_f32 v232, v229, s8, -v232
	v_fmac_f32_e32 v232, 0x3377d1cf, v229
	v_fmac_f32_e32 v232, 0x3f317217, v229
	v_mov_b32_e32 v229, v232
	v_add_f32_e32 v231, v231, v229
	v_add_u32_e32 v229, 14, v226
	v_cmp_lt_i32_e32 vcc, v229, v183
	v_fma_f32 v78, v78, s70, -v231
	v_add_u32_e32 v226, 15, v226
	v_cndmask_b32_e64 v229, 0, -v231, vcc
	v_mul_f32_e32 v231, 0x3db504f3, v79
	v_max_f32_e32 v232, 0, v231
	v_mul_f32_e64 v231, |v231|, s71
	v_exp_f32_e32 v231, v231
	v_cndmask_b32_e32 v78, v199, v78, vcc
	v_add_f32_e32 v230, v229, v230
	v_add_f32_e32 v231, 1.0, v231
	v_log_f32_e32 v231, v231
	s_nop 0
	v_mul_f32_e32 v233, 0x3f317217, v231
	v_fma_f32 v233, v231, s8, -v233
	v_fmac_f32_e32 v233, 0x3377d1cf, v231
	v_fmac_f32_e32 v233, 0x3f317217, v231
	v_mov_b32_e32 v231, v233
	v_add_f32_e32 v231, v232, v231
	v_cmp_lt_i32_e32 vcc, v226, v183
	v_fma_f32 v79, v79, s70, -v231
	s_nop 0
	v_cndmask_b32_e64 v226, 0, -v231, vcc
	v_add_f32_e32 v230, v226, v230
	ds_bpermute_b32 v231, v180, v230
	v_cndmask_b32_e32 v79, v199, v79, vcc
	s_waitcnt lgkmcnt(0)
; DI unsigned cvt_pk_bf16(float lo, float hi) { const f32x2 v = {lo, hi}; const bf16x2_t b = __builtin_convertvector(v, bf16x2_t); return __builtin_bit_cast(unsigned, b); }
; #define MFMA32(a, b, c) __builtin_amdgcn_mfma_f32_32x32x16_bf16((a), (b), (c), 0, 0, 0)
; template <bool SAMP> DI void attn_wave_unit(const Params& p, int u, int lane_) {
;     ...
;         const float ptot = __shfl_xor(tot, 32);
;         float tb = carry + (hh == 0 ? ptot : 0.f);
;         float w[16];
; #pragma unroll
;         for (int i = 15; i >= 0; --i) { w[i] = __expf(zz[i] + tb); tb += lr[i]; }
;         carry += tot + ptot;
;         bf16x8 pf[2];
; #pragma unroll
;         for (int s = 0; s < 2; ++s) { u32x4 t; t.x = cvt_pk_bf16(w[8 * s], w[8 * s + 1]); t.y = cvt_pk_bf16(w[8 * s + 2], w[8 * s + 3]); t.z = cvt_pk_bf16(w[8 * s + 4], w[8 * s + 5]); t.w = cvt_pk_bf16(w[8 * s + 6], w[8 * s + 7]);
;             pf[s] = __builtin_bit_cast(bf16x8, t); }
; #pragma unroll
;         for (int d = 0; d < 4; ++d)
; #pragma unroll
;             for (int s = 0; s < 2; ++s) oacc[d] = MFMA32(vf[2 * d + s], pf[s], oacc[d]);
;         if (__all(carry < -110.f)) break;
	v_cndmask_b32_e64 v232, 0, v231, s[38:39]
	v_add_f32_e32 v232, v214, v232
	v_add_f32_e32 v226, v226, v232
	v_add_f32_e32 v78, v78, v226
	v_add_f32_e32 v226, v229, v226
	v_add_f32_e32 v77, v77, v226
	v_add_f32_e32 v226, v228, v226
	v_add_f32_e32 v76, v76, v226
	v_add_f32_e32 v226, v227, v226
	v_add_f32_e32 v225, v225, v226
	v_add_f32_e32 v224, v224, v225
	v_add_f32_e32 v223, v223, v224
	v_add_f32_e32 v222, v222, v223
	v_add_f32_e32 v221, v221, v222
	v_add_f32_e32 v220, v220, v221
	v_add_f32_e32 v219, v219, v220
	v_add_f32_e32 v218, v218, v219
	v_add_f32_e32 v217, v217, v218
	v_add_f32_e32 v216, v216, v217
	v_add_f32_e32 v215, v215, v216
	v_add_f32_e32 v71, v71, v222
	v_add_f32_e32 v70, v70, v221
	v_add_f32_e32 v69, v69, v220
	v_add_f32_e32 v68, v68, v219
	v_add_f32_e32 v67, v67, v218
	v_add_f32_e32 v66, v66, v217
	v_add_f32_e32 v65, v65, v216
	v_add_f32_e32 v64, v64, v215
	v_mul_f32_e32 v71, 0x3fb8aa3b, v71
	v_mul_f32_e32 v70, 0x3fb8aa3b, v70
	v_mul_f32_e32 v69, 0x3fb8aa3b, v69
	v_mul_f32_e32 v68, 0x3fb8aa3b, v68
	v_mul_f32_e32 v67, 0x3fb8aa3b, v67
	v_mul_f32_e32 v66, 0x3fb8aa3b, v66
	v_mul_f32_e32 v65, 0x3fb8aa3b, v65
	v_mul_f32_e32 v64, 0x3fb8aa3b, v64
	v_exp_f32_e32 v71, v71
	v_exp_f32_e32 v70, v70
	v_exp_f32_e32 v69, v69
	v_exp_f32_e32 v68, v68
	v_exp_f32_e32 v67, v67
	v_exp_f32_e32 v66, v66
	v_exp_f32_e32 v65, v65
	v_exp_f32_e32 v64, v64
	v_add_f32_e32 v79, v79, v232
	v_add_f32_e32 v75, v75, v226
	v_add_f32_e32 v74, v74, v225
	v_cvt_pk_bf16_f32 v64, v64, v65
	v_cvt_pk_bf16_f32 v65, v66, v67
	v_cvt_pk_bf16_f32 v66, v68, v69
	v_cvt_pk_bf16_f32 v67, v70, v71
	v_add_f32_e32 v73, v73, v224
	v_add_f32_e32 v72, v72, v223
	s_waitcnt vmcnt(13)
	v_mfma_f32_32x32x16_bf16 v[0:15], v[172:175], v[64:67], v[0:15]
	v_mul_f32_e32 v79, 0x3fb8aa3b, v79
	v_mul_f32_e32 v78, 0x3fb8aa3b, v78
	v_mul_f32_e32 v77, 0x3fb8aa3b, v77
	v_mul_f32_e32 v76, 0x3fb8aa3b, v76
	v_mul_f32_e32 v75, 0x3fb8aa3b, v75
	v_mul_f32_e32 v74, 0x3fb8aa3b, v74
	v_mul_f32_e32 v73, 0x3fb8aa3b, v73
	v_mfma_f32_32x32x16_bf16 v[16:31], v[160:163], v[64:67], v[16:31]
	v_mul_f32_e32 v72, 0x3fb8aa3b, v72
	v_exp_f32_e32 v79, v79
	v_exp_f32_e32 v78, v78
	v_exp_f32_e32 v77, v77
	v_exp_f32_e32 v76, v76
	v_exp_f32_e32 v75, v75
	v_exp_f32_e32 v74, v74
	s_waitcnt vmcnt(11)
	v_mfma_f32_32x32x16_bf16 v[32:47], v[152:155], v[64:67], v[32:47]
	v_exp_f32_e32 v73, v73
	v_exp_f32_e32 v72, v72
	v_add_f32_e32 v215, v230, v231
	v_cvt_pk_bf16_f32 v69, v74, v75
	v_cvt_pk_bf16_f32 v70, v76, v77
	v_cvt_pk_bf16_f32 v68, v72, v73
	v_cvt_pk_bf16_f32 v71, v78, v79
	s_waitcnt vmcnt(9)
	v_mfma_f32_32x32x16_bf16 v[48:63], v[144:147], v[64:67], v[48:63]
	v_add_f32_e32 v214, v214, v215
	v_cmp_gt_f32_e32 vcc, s10, v214
	s_cmp_lg_u64 vcc, exec
	s_cselect_b64 s[0:1], -1, 0
	s_add_i32 s20, s20, -1
	s_cmp_lg_u32 s92, s18
	s_cselect_b64 s[24:25], -1, 0
	v_mfma_f32_32x32x16_bf16 v[0:15], v[168:171], v[68:71], v[0:15]
	s_and_b64 s[0:1], s[24:25], s[0:1]
	s_add_u32 s18, s18, 0x2000
	s_addc_u32 s19, s19, 0
	s_sub_i32 s21, s21, 32
	s_and_b64 vcc, exec, s[0:1]
	v_mfma_f32_32x32x16_bf16 v[16:31], v[164:167], v[68:71], v[16:31]
	v_mfma_f32_32x32x16_bf16 v[32:47], v[156:159], v[68:71], v[32:47]
	s_waitcnt vmcnt(8)
	v_mfma_f32_32x32x16_bf16 v[48:63], v[148:151], v[68:71], v[48:63]
	s_cbranch_vccnz .LBB0_187
	v_or_b32_e32 v64, s17, v182
	s_mov_b64 s[0:1], 0

; template <bool SAMP> DI void attn_wave_unit(const Params& p, int u, int lane_) {
;     ...
;         const int kbase = kt * 32 + 16 * hh;
;         float tot = 0.f;
; #pragma unroll
;         for (int i = 0; i < 16; ++i) { const float z = st[i] * scale;
;             const float sp = fmaxf(z, 0.f) + __logf(1.f + __expf(-fabsf(z)));
;             const bool valid = (kbase + i) < qpos; lr[i] = valid ? -sp : 0.f; zz[i] = valid ? (z - sp) : -1e30f; tot += lr[i]; }
.LBB0_191:
	s_add_i32 s20, s26, s18
	s_nop 0
	v_mul_f32_e32 v222, 0x3db504f3, v64
	v_max_f32_e32 v223, 0, v222
	v_mul_f32_e64 v222, |v222|, s71
	v_exp_f32_e32 v222, v222
	v_add_u32_e32 v180, s25, v219
	v_add_u32_e32 v221, 0x400, v180
	v_lshl_add_u64 v[182:183], v[182:183], 0, s[94:95]
	v_add_f32_e32 v222, 1.0, v222
	v_log_f32_e32 v222, v222
	s_nop 0
	v_mul_f32_e32 v224, 0x3f317217, v222
	v_fma_f32 v224, v222, s8, -v224
	v_fmac_f32_e32 v224, 0x3377d1cf, v222
	v_fmac_f32_e32 v224, 0x3f317217, v222
	v_mov_b32_e32 v222, v224
	v_add_f32_e32 v222, v223, v222
	v_cmp_lt_i32_e32 vcc, v221, v215
	v_sub_f32_e32 v221, 0, v222
	v_fma_f32 v64, v64, s70, -v222
	v_cndmask_b32_e32 v222, 0, v221, vcc
	v_mul_f32_e32 v221, 0x3db504f3, v65
	v_max_f32_e32 v223, 0, v221
	v_mul_f32_e64 v221, |v221|, s71
	v_exp_f32_e32 v221, v221
	v_cndmask_b32_e32 v64, v199, v64, vcc
	v_add_f32_e32 v221, 1.0, v221
	v_log_f32_e32 v221, v221
	s_nop 0
	v_mul_f32_e32 v224, 0x3f317217, v221
	v_fma_f32 v224, v221, s8, -v224
	v_fmac_f32_e32 v224, 0x3377d1cf, v221
	v_fmac_f32_e32 v224, 0x3f317217, v221
	v_mov_b32_e32 v221, v224
	v_add_f32_e32 v223, v223, v221
	v_add_u32_e32 v221, 0x401, v180
	v_cmp_lt_i32_e32 vcc, v221, v215
	v_fma_f32 v65, v65, s70, -v223
	s_nop 0
	v_cndmask_b32_e64 v221, 0, -v223, vcc
	v_add_f32_e32 v223, v221, v222
	v_mul_f32_e32 v222, 0x3db504f3, v66
	v_max_f32_e32 v224, 0, v222
	v_mul_f32_e64 v222, |v222|, s71
	v_exp_f32_e32 v222, v222
	v_cndmask_b32_e32 v65, v199, v65, vcc
	v_add_f32_e32 v222, 1.0, v222
	v_log_f32_e32 v222, v222
	s_nop 0
	v_mul_f32_e32 v225, 0x3f317217, v222
	v_fma_f32 v225, v222, s8, -v225
	v_fmac_f32_e32 v225, 0x3377d1cf, v222
	v_fmac_f32_e32 v225, 0x3f317217, v222
	v_mov_b32_e32 v222, v225
	v_add_f32_e32 v224, v224, v222
	v_add_u32_e32 v222, 0x402, v180
	v_cmp_lt_i32_e32 vcc, v222, v215
	v_fma_f32 v66, v66, s70, -v224
	s_nop 0
	v_cndmask_b32_e64 v222, 0, -v224, vcc
	v_add_f32_e32 v224, v222, v223
	v_mul_f32_e32 v223, 0x3db504f3, v67
	v_max_f32_e32 v225, 0, v223
	v_mul_f32_e64 v223, |v223|, s71
	v_exp_f32_e32 v223, v223
	v_cndmask_b32_e32 v66, v199, v66, vcc
	v_add_f32_e32 v223, 1.0, v223
	v_log_f32_e32 v223, v223
	s_nop 0
	v_mul_f32_e32 v226, 0x3f317217, v223
	v_fma_f32 v226, v223, s8, -v226
	v_fmac_f32_e32 v226, 0x3377d1cf, v223
	v_fmac_f32_e32 v226, 0x3f317217, v223
	v_mov_b32_e32 v223, v226
	v_add_f32_e32 v225, v225, v223
	v_add_u32_e32 v223, 0x403, v180
	v_cmp_lt_i32_e32 vcc, v223, v215
	v_fma_f32 v67, v67, s70, -v225
	s_nop 0
	v_cndmask_b32_e64 v223, 0, -v225, vcc
	v_add_f32_e32 v225, v223, v224
	v_mul_f32_e32 v224, 0x3db504f3, v68
	v_max_f32_e32 v226, 0, v224
	v_mul_f32_e64 v224, |v224|, s71
	v_exp_f32_e32 v224, v224
	v_cndmask_b32_e32 v67, v199, v67, vcc
	v_add_f32_e32 v224, 1.0, v224
	v_log_f32_e32 v224, v224
	s_nop 0
	v_mul_f32_e32 v227, 0x3f317217, v224
	v_fma_f32 v227, v224, s8, -v227
	v_fmac_f32_e32 v227, 0x3377d1cf, v224
	v_fmac_f32_e32 v227, 0x3f317217, v224
	v_mov_b32_e32 v224, v227
	v_add_f32_e32 v226, v226, v224
	v_add_u32_e32 v224, 0x404, v180
	v_cmp_lt_i32_e32 vcc, v224, v215
	v_fma_f32 v68, v68, s70, -v226
	s_nop 0
	v_cndmask_b32_e64 v224, 0, -v226, vcc
	v_add_f32_e32 v226, v224, v225
	v_mul_f32_e32 v225, 0x3db504f3, v69
	v_max_f32_e32 v227, 0, v225
	v_mul_f32_e64 v225, |v225|, s71
	v_exp_f32_e32 v225, v225
	v_cndmask_b32_e32 v68, v199, v68, vcc
	v_add_f32_e32 v225, 1.0, v225
	v_log_f32_e32 v225, v225
	s_nop 0
	v_mul_f32_e32 v228, 0x3f317217, v225
	v_fma_f32 v228, v225, s8, -v228
	v_fmac_f32_e32 v228, 0x3377d1cf, v225
	v_fmac_f32_e32 v228, 0x3f317217, v225
	v_mov_b32_e32 v225, v228
	v_add_f32_e32 v227, v227, v225
	v_add_u32_e32 v225, 0x405, v180
	v_cmp_lt_i32_e32 vcc, v225, v215
	v_fma_f32 v69, v69, s70, -v227
	s_nop 0
	v_cndmask_b32_e64 v225, 0, -v227, vcc
	v_add_f32_e32 v227, v225, v226
	v_mul_f32_e32 v226, 0x3db504f3, v70
	v_max_f32_e32 v228, 0, v226
	v_mul_f32_e64 v226, |v226|, s71
	v_exp_f32_e32 v226, v226
	v_cndmask_b32_e32 v69, v199, v69, vcc
	v_add_f32_e32 v226, 1.0, v226
	v_log_f32_e32 v226, v226
	s_nop 0
	v_mul_f32_e32 v229, 0x3f317217, v226
	v_fma_f32 v229, v226, s8, -v229
	v_fmac_f32_e32 v229, 0x3377d1cf, v226
	v_fmac_f32_e32 v229, 0x3f317217, v226
	v_mov_b32_e32 v226, v229
	v_add_f32_e32 v228, v228, v226
	v_add_u32_e32 v226, 0x406, v180
	v_cmp_lt_i32_e32 vcc, v226, v215
	v_fma_f32 v70, v70, s70, -v228
	s_nop 0
	v_cndmask_b32_e64 v226, 0, -v228, vcc
	v_add_f32_e32 v228, v226, v227
	v_mul_f32_e32 v227, 0x3db504f3, v71
	v_max_f32_e32 v229, 0, v227
	v_mul_f32_e64 v227, |v227|, s71
	v_exp_f32_e32 v227, v227
	v_cndmask_b32_e32 v70, v199, v70, vcc
	v_add_f32_e32 v227, 1.0, v227
	v_log_f32_e32 v227, v227
	s_nop 0
	v_mul_f32_e32 v230, 0x3f317217, v227
	v_fma_f32 v230, v227, s8, -v230
	v_fmac_f32_e32 v230, 0x3377d1cf, v227
	v_fmac_f32_e32 v230, 0x3f317217, v227
	v_mov_b32_e32 v227, v230
	v_add_f32_e32 v229, v229, v227
	v_add_u32_e32 v227, 0x407, v180
	v_cmp_lt_i32_e32 vcc, v227, v215
	v_fma_f32 v71, v71, s70, -v229
	s_nop 0
	v_cndmask_b32_e64 v227, 0, -v229, vcc
	v_add_f32_e32 v229, v227, v228
	v_mul_f32_e32 v228, 0x3db504f3, v72
	v_max_f32_e32 v230, 0, v228
	v_mul_f32_e64 v228, |v228|, s71
	v_exp_f32_e32 v228, v228
	v_cndmask_b32_e32 v71, v199, v71, vcc
	v_add_f32_e32 v228, 1.0, v228
	v_log_f32_e32 v228, v228
	s_nop 0
	v_mul_f32_e32 v231, 0x3f317217, v228
	v_fma_f32 v231, v228, s8, -v231
	v_fmac_f32_e32 v231, 0x3377d1cf, v228
	v_fmac_f32_e32 v231, 0x3f317217, v228
	v_mov_b32_e32 v228, v231
	v_add_f32_e32 v230, v230, v228
	v_add_u32_e32 v228, 0x408, v180
	v_cmp_lt_i32_e32 vcc, v228, v215
	v_fma_f32 v72, v72, s70, -v230
	s_nop 0
	v_cndmask_b32_e64 v228, 0, -v230, vcc
	v_add_f32_e32 v230, v228, v229
	v_mul_f32_e32 v229, 0x3db504f3, v73
; template <bool SAMP> DI void attn_wave_unit(const Params& p, int u, int lane_) {
;     ...
;         const int kbase = kt * 32 + 16 * hh;
;         float tot = 0.f;
; #pragma unroll
;         for (int i = 0; i < 16; ++i) { const float z = st[i] * scale;
;             const float sp = fmaxf(z, 0.f) + __logf(1.f + __expf(-fabsf(z)));
;             const bool valid = (kbase + i) < qpos; lr[i] = valid ? -sp : 0.f; zz[i] = valid ? (z - sp) : -1e30f; tot += lr[i]; }
	v_max_f32_e32 v231, 0, v229
	v_mul_f32_e64 v229, |v229|, s71
	v_exp_f32_e32 v229, v229
	v_cndmask_b32_e32 v72, v199, v72, vcc
	v_add_f32_e32 v229, 1.0, v229
	v_log_f32_e32 v229, v229
	s_nop 0
	v_mul_f32_e32 v232, 0x3f317217, v229
	v_fma_f32 v232, v229, s8, -v232
	v_fmac_f32_e32 v232, 0x3377d1cf, v229
	v_fmac_f32_e32 v232, 0x3f317217, v229
	v_mov_b32_e32 v229, v232
	v_add_f32_e32 v231, v231, v229
	v_add_u32_e32 v229, 0x409, v180
	v_cmp_lt_i32_e32 vcc, v229, v215
	v_fma_f32 v73, v73, s70, -v231
	s_nop 0
	v_cndmask_b32_e64 v229, 0, -v231, vcc
	v_mul_f32_e32 v231, 0x3db504f3, v74
	v_max_f32_e32 v232, 0, v231
	v_mul_f32_e64 v231, |v231|, s71
	v_exp_f32_e32 v231, v231
	v_cndmask_b32_e32 v73, v199, v73, vcc
	v_add_f32_e32 v230, v229, v230
	v_add_f32_e32 v231, 1.0, v231
	v_log_f32_e32 v231, v231
	s_nop 0
	v_mul_f32_e32 v233, 0x3f317217, v231
	v_fma_f32 v233, v231, s8, -v233
	v_fmac_f32_e32 v233, 0x3377d1cf, v231
	v_fmac_f32_e32 v233, 0x3f317217, v231
	v_mov_b32_e32 v231, v233
	v_add_f32_e32 v231, v232, v231
	v_add_u32_e32 v232, 0x40a, v180
	v_cmp_lt_i32_e32 vcc, v232, v215
	v_fma_f32 v74, v74, s70, -v231
	s_nop 0
	v_cndmask_b32_e64 v232, 0, -v231, vcc
	v_mul_f32_e32 v231, 0x3db504f3, v75
	v_max_f32_e32 v233, 0, v231
	v_mul_f32_e64 v231, |v231|, s71
	v_exp_f32_e32 v231, v231
	v_cndmask_b32_e32 v74, v199, v74, vcc
	v_add_f32_e32 v230, v232, v230
	v_add_f32_e32 v231, 1.0, v231
	v_log_f32_e32 v231, v231
	s_nop 0
	v_mul_f32_e32 v234, 0x3f317217, v231
	v_fma_f32 v234, v231, s8, -v234
	v_fmac_f32_e32 v234, 0x3377d1cf, v231
	v_fmac_f32_e32 v234, 0x3f317217, v231
	v_mov_b32_e32 v231, v234
	v_add_f32_e32 v231, v233, v231
	v_add_u32_e32 v233, 0x40b, v180
	v_cmp_lt_i32_e32 vcc, v233, v215
	v_fma_f32 v75, v75, s70, -v231
	s_nop 0
	v_cndmask_b32_e64 v233, 0, -v231, vcc
	v_mul_f32_e32 v231, 0x3db504f3, v76
	v_max_f32_e32 v234, 0, v231
	v_mul_f32_e64 v231, |v231|, s71
	v_exp_f32_e32 v231, v231
	v_cndmask_b32_e32 v75, v199, v75, vcc
	v_add_f32_e32 v230, v233, v230
	v_add_f32_e32 v231, 1.0, v231
	v_log_f32_e32 v231, v231
	s_nop 0
	v_mul_f32_e32 v235, 0x3f317217, v231
	v_fma_f32 v235, v231, s8, -v235
	v_fmac_f32_e32 v235, 0x3377d1cf, v231
	v_fmac_f32_e32 v235, 0x3f317217, v231
	v_mov_b32_e32 v231, v235
	v_add_f32_e32 v231, v234, v231
	v_add_u32_e32 v234, 0x40c, v180
	v_cmp_lt_i32_e32 vcc, v234, v215
	v_fma_f32 v76, v76, s70, -v231
	s_nop 0
	v_cndmask_b32_e64 v234, 0, -v231, vcc
	v_mul_f32_e32 v231, 0x3db504f3, v77
	v_max_f32_e32 v235, 0, v231
	v_mul_f32_e64 v231, |v231|, s71
	v_exp_f32_e32 v231, v231
	v_cndmask_b32_e32 v76, v199, v76, vcc
	v_add_f32_e32 v230, v234, v230
	v_add_f32_e32 v231, 1.0, v231
	v_log_f32_e32 v231, v231
	s_nop 0
	v_mul_f32_e32 v236, 0x3f317217, v231
	v_fma_f32 v236, v231, s8, -v236
	v_fmac_f32_e32 v236, 0x3377d1cf, v231
	v_fmac_f32_e32 v236, 0x3f317217, v231
	v_mov_b32_e32 v231, v236
	v_add_f32_e32 v231, v235, v231
	v_add_u32_e32 v235, 0x40d, v180
	v_cmp_lt_i32_e32 vcc, v235, v215
	v_fma_f32 v77, v77, s70, -v231
	s_nop 0
	v_cndmask_b32_e64 v235, 0, -v231, vcc
	v_mul_f32_e32 v231, 0x3db504f3, v78
	v_max_f32_e32 v236, 0, v231
	v_mul_f32_e64 v231, |v231|, s71
	v_exp_f32_e32 v231, v231
	v_cndmask_b32_e32 v77, v199, v77, vcc
	v_add_f32_e32 v230, v235, v230
	v_add_f32_e32 v231, 1.0, v231
	v_log_f32_e32 v231, v231
	s_nop 0
	v_mul_f32_e32 v237, 0x3f317217, v231
	v_fma_f32 v237, v231, s8, -v237
	v_fmac_f32_e32 v237, 0x3377d1cf, v231
	v_fmac_f32_e32 v237, 0x3f317217, v231
	v_mov_b32_e32 v231, v237
	v_add_f32_e32 v231, v236, v231
	v_add_u32_e32 v236, 0x40e, v180
	v_cmp_lt_i32_e32 vcc, v236, v215
	v_fma_f32 v78, v78, s70, -v231
	v_add_u32_e32 v180, 0x40f, v180
	v_cndmask_b32_e64 v236, 0, -v231, vcc
	v_mul_f32_e32 v231, 0x3db504f3, v79
	v_max_f32_e32 v237, 0, v231
	v_mul_f32_e64 v231, |v231|, s71
	v_exp_f32_e32 v231, v231
	v_cndmask_b32_e32 v78, v199, v78, vcc
	v_add_f32_e32 v230, v236, v230
	v_add_f32_e32 v231, 1.0, v231
	v_log_f32_e32 v231, v231
	s_nop 0
	v_mul_f32_e32 v238, 0x3f317217, v231
	v_fma_f32 v238, v231, s8, -v238
	v_fmac_f32_e32 v238, 0x3377d1cf, v231
	v_fmac_f32_e32 v238, 0x3f317217, v231
	v_mov_b32_e32 v231, v238
	v_add_f32_e32 v231, v237, v231
	v_cmp_lt_i32_e32 vcc, v180, v215
	v_fma_f32 v79, v79, s70, -v231
	s_nop 0
	v_cndmask_b32_e64 v180, 0, -v231, vcc
	v_add_f32_e32 v230, v180, v230
	ds_bpermute_b32 v231, v216, v230
	v_cndmask_b32_e32 v79, v199, v79, vcc
	s_waitcnt lgkmcnt(0)
; DI unsigned cvt_pk_bf16(float lo, float hi) { const f32x2 v = {lo, hi}; const bf16x2_t b = __builtin_convertvector(v, bf16x2_t); return __builtin_bit_cast(unsigned, b); }
; #define MFMA32(a, b, c) __builtin_amdgcn_mfma_f32_32x32x16_bf16((a), (b), (c), 0, 0, 0)
; template <bool SAMP> DI void attn_wave_unit(const Params& p, int u, int lane_) {
;     ...
;         const float ptot = __shfl_xor(tot, 32);
;         float tb = carry + (hh == 0 ? ptot : 0.f);
;         float w[16];
; #pragma unroll
;         for (int i = 15; i >= 0; --i) { w[i] = __expf(zz[i] + tb); tb += lr[i]; }
;         carry += tot + ptot;
;         bf16x8 pf[2];
; #pragma unroll
;         for (int s = 0; s < 2; ++s) { u32x4 t; t.x = cvt_pk_bf16(w[8 * s], w[8 * s + 1]); t.y = cvt_pk_bf16(w[8 * s + 2], w[8 * s + 3]); t.z = cvt_pk_bf16(w[8 * s + 4], w[8 * s + 5]); t.w = cvt_pk_bf16(w[8 * s + 6], w[8 * s + 7]);
;             pf[s] = __builtin_bit_cast(bf16x8, t); }
; #pragma unroll
;         for (int d = 0; d < 4; ++d)
; #pragma unroll
;             for (int s = 0; s < 2; ++s) oacc[d] = MFMA32(vf[2 * d + s], pf[s], oacc[d]);
;         if (__all(carry < -110.f)) break;
	v_cndmask_b32_e64 v237, 0, v231, s[38:39]
	v_add_f32_e32 v237, v220, v237
	v_add_f32_e32 v180, v180, v237
	v_add_f32_e32 v78, v78, v180
	v_add_f32_e32 v180, v236, v180
	v_add_f32_e32 v77, v77, v180
	v_add_f32_e32 v180, v235, v180
	v_add_f32_e32 v76, v76, v180
	v_add_f32_e32 v180, v234, v180
	v_add_f32_e32 v75, v75, v180
	v_add_f32_e32 v180, v233, v180
	v_add_f32_e32 v74, v74, v180
	v_add_f32_e32 v180, v232, v180
	v_add_f32_e32 v73, v73, v180
	v_add_f32_e32 v180, v229, v180
	v_add_f32_e32 v72, v72, v180
	v_add_f32_e32 v180, v228, v180
	v_add_f32_e32 v71, v71, v180
	v_add_f32_e32 v180, v227, v180
	v_add_f32_e32 v70, v70, v180
	v_add_f32_e32 v180, v226, v180
	v_add_f32_e32 v69, v69, v180
	v_add_f32_e32 v180, v225, v180
	v_add_f32_e32 v68, v68, v180
	v_add_f32_e32 v180, v224, v180
	v_add_f32_e32 v67, v67, v180
	v_add_f32_e32 v180, v223, v180
	v_add_f32_e32 v66, v66, v180
	v_add_f32_e32 v180, v222, v180
	v_add_f32_e32 v65, v65, v180
	v_add_f32_e32 v180, v221, v180
	v_add_f32_e32 v64, v64, v180
	v_mul_f32_e32 v71, 0x3fb8aa3b, v71
	v_mul_f32_e32 v70, 0x3fb8aa3b, v70
	v_mul_f32_e32 v69, 0x3fb8aa3b, v69
	v_mul_f32_e32 v68, 0x3fb8aa3b, v68
	v_mul_f32_e32 v67, 0x3fb8aa3b, v67
	v_mul_f32_e32 v66, 0x3fb8aa3b, v66
	v_mul_f32_e32 v65, 0x3fb8aa3b, v65
	v_mul_f32_e32 v64, 0x3fb8aa3b, v64
	v_exp_f32_e32 v71, v71
	v_exp_f32_e32 v70, v70
	v_exp_f32_e32 v69, v69
	v_exp_f32_e32 v68, v68
	v_exp_f32_e32 v67, v67
	v_exp_f32_e32 v66, v66
	v_exp_f32_e32 v65, v65
	v_exp_f32_e32 v64, v64
	v_add_f32_e32 v79, v79, v237
	v_mul_f32_e32 v79, 0x3fb8aa3b, v79
	v_mul_f32_e32 v78, 0x3fb8aa3b, v78
	v_cvt_pk_bf16_f32 v64, v64, v65
	v_cvt_pk_bf16_f32 v65, v66, v67
	v_cvt_pk_bf16_f32 v66, v68, v69
	v_cvt_pk_bf16_f32 v67, v70, v71
	v_mul_f32_e32 v77, 0x3fb8aa3b, v77
	v_mul_f32_e32 v76, 0x3fb8aa3b, v76
	s_waitcnt vmcnt(7)
	v_mfma_f32_32x32x16_bf16 v[0:15], v[140:143], v[64:67], v[0:15]
	v_mul_f32_e32 v75, 0x3fb8aa3b, v75
	v_mul_f32_e32 v74, 0x3fb8aa3b, v74
	v_mul_f32_e32 v73, 0x3fb8aa3b, v73
	v_mul_f32_e32 v72, 0x3fb8aa3b, v72
	v_exp_f32_e32 v79, v79
	v_exp_f32_e32 v78, v78
	v_exp_f32_e32 v77, v77
	s_waitcnt vmcnt(5)
	v_mfma_f32_32x32x16_bf16 v[16:31], v[144:147], v[64:67], v[16:31]
	v_exp_f32_e32 v76, v76
	v_exp_f32_e32 v75, v75
	v_exp_f32_e32 v74, v74
	v_exp_f32_e32 v73, v73
	v_exp_f32_e32 v72, v72
	v_add_f32_e32 v180, v230, v231
	v_cvt_pk_bf16_f32 v69, v74, v75
	s_waitcnt vmcnt(3)
	v_mfma_f32_32x32x16_bf16 v[32:47], v[156:159], v[64:67], v[32:47]
	v_cvt_pk_bf16_f32 v68, v72, v73
	v_cvt_pk_bf16_f32 v70, v76, v77
	v_cvt_pk_bf16_f32 v71, v78, v79
	v_add_f32_e32 v220, v220, v180
	v_cmp_gt_f32_e32 vcc, s10, v220
	s_cmp_lg_u64 vcc, exec
	s_cselect_b64 s[0:1], -1, 0
	s_waitcnt vmcnt(1)
	v_mfma_f32_32x32x16_bf16 v[48:63], v[164:167], v[64:67], v[48:63]
	s_add_i32 s24, s24, -1
	s_cmp_lg_u32 s20, 0
	s_cselect_b64 s[20:21], -1, 0
	s_and_b64 s[0:1], s[20:21], s[0:1]
	s_add_i32 s16, s16, -1
	s_add_u32 s18, s18, 0xffffc000
	s_addc_u32 s19, s19, -1
	v_mfma_f32_32x32x16_bf16 v[0:15], v[136:139], v[68:71], v[0:15]
	s_sub_i32 s25, s25, 32
	s_and_b64 vcc, exec, s[0:1]
	v_mfma_f32_32x32x16_bf16 v[16:31], v[148:151], v[68:71], v[16:31]
	v_mfma_f32_32x32x16_bf16 v[32:47], v[160:163], v[68:71], v[32:47]
	s_waitcnt vmcnt(0)
	v_mfma_f32_32x32x16_bf16 v[48:63], v[168:171], v[68:71], v[48:63]
	s_cbranch_vccz .LBB0_177

; #define SC_STEP(st, RL, RW) do { SC_LOAD(RL, (st) + 3); SC_WRITE(RW, ((st) + 1) & 1); __syncthreads(); } while (0)
; DI void scan_unit(const Params& p, unsigned char* lds, int chunk0, int nsteps, int bh_b, int h, int slice, bool samp) {
;     ...
;         for (int st = 0; st < nst3; st += 3) {
;             SC_STEP(st, r0, r1);
;             SC_STEP(st + 1, r1, r2);
;             SC_STEP(st + 2, r2, r0);
;         }
.LBB0_663:
	s_or_b64 exec, exec, s[20:21]
	s_cmpk_lt_u32 s16, 0x7e
	s_mov_b32 s16, s17
	s_waitcnt lgkmcnt(0)
	s_barrier
	s_cbranch_scc0 .LBB0_670

; #define MFMA16(a, b, c) __builtin_amdgcn_mfma_f32_16x16x32_bf16((a), (b), (c), 0, 0, 0)
; DI void scan_unit(const Params& p, unsigned char* lds, int chunk0, int nsteps, int bh_b, int h, int slice, bool samp) {
;     ...
;         for (int st = 0; st < nst3; ++st) {
;             if (st >= 1 && st - 1 < nsteps) {
;                 const bf16x8 v0 = XV[(((st - 1) & 1) * 2 + 0) * 64 + lane], v1 = XV[(((st - 1) & 1) * 2 + 1) * 64 + lane];
; #pragma unroll
;                 for (int rt = 0; rt < 4; ++rt) { oa[rt] = MFMA16(qk[2 * rt], v0, oa[rt]); oa[rt] = MFMA16(qk[2 * rt + 1], v1, oa[rt]); }
;                 const int tok0 = (chunk0 + st - 1) * 64;
; #pragma unroll
;                 for (int rt = 0; rt < 4; ++rt)
; #pragma unroll
;                     for (int j = 0; j < 4; ++j) Obuf[(size_t)(tok0 + 16 * rt + 4 * q4 + j) * 512 + h * 128 + slice * 16 + n16] = oa[rt][j];
;             }
;             if (st < nsteps) {
;                 const unsigned char* L = lds + (st & 1) * 59392;
;                 bf16x8 sbv[4];
; #pragma unroll
;                 for (int s = 0; s < 4; ++s) sbv[s] = XS[((st & 1) * 4 + s) * 64 + lane];
; #pragma unroll
;                 for (int rt = 0; rt < 4; ++rt) oa[rt] = (f32x4){0.f, 0.f, 0.f, 0.f};
; #pragma unroll
;                 for (int half = 0; half < 2; ++half) {
;                     bf16x8 fq[8];
; #pragma unroll
;                     for (int rt = 0; rt < 4; ++rt) { fq[2 * rt] = *(const bf16x8*)(L + 16384 + ((rt * 4 + 2 * half) * 64 + lane) * 16); fq[2 * rt + 1] = *(const bf16x8*)(L + 16384 + ((rt * 4 + 2 * half + 1) * 64 + lane) * 16); }
;                     __builtin_amdgcn_sched_barrier(0);
; #pragma unroll
;                     for (int ds = 0; ds < 2; ++ds)
; #pragma unroll
;                         for (int rt = 0; rt < 4; ++rt) oa[rt] = MFMA16(fq[2 * rt + ds], sbv[2 * half + ds], oa[rt]);
;                     __builtin_amdgcn_sched_barrier(0);
;                 }
; #pragma unroll
;                 for (int i = 0; i < 8; ++i) qk[i] = *(const bf16x8*)(L + 49152 + (i * 64 + lane) * 16);
;             }
;             __syncthreads();
;         }
.LBB0_672:
	s_add_i32 s20, s20, 1
	s_add_i32 s17, s17, 64
	s_addk_i32 s16, 0x80
	s_cmpk_eq_i32 s17, 0x2040
	s_waitcnt lgkmcnt(0)
	s_barrier
	s_cbranch_scc1 .LBB0_677

; DI void scan_unit(const Params& p, unsigned char* lds, int chunk0, int nsteps, int bh_b, int h, int slice, bool samp) {
;     ...
;         for (int st = 0; st < nst3; ++st) {
;             if (st < nsteps) {
;                 const unsigned char* L = lds + (st & 1) * 59392;
;                 const float gl = GLS[st];
;                 bf16x8 fa[8], fb[8];
; #pragma unroll
;                 for (int rt = 0; rt < 4; ++rt) { fa[2 * rt] = *(const bf16x8*)(L + ((rt * 4 + 0) * 64 + lane) * 16); fa[2 * rt + 1] = *(const bf16x8*)(L + ((rt * 4 + 1) * 64 + lane) * 16);
;                     fb[2 * rt] = *(const bf16x8*)(L + ((rt * 4 + 2) * 64 + lane) * 16); fb[2 * rt + 1] = *(const bf16x8*)(L + ((rt * 4 + 3) * 64 + lane) * 16); }
;                 f32x4 va[4];
; #pragma unroll
;                 for (int rt = 0; rt < 4; ++rt) va[rt] = (f32x4){0.f, 0.f, 0.f, 0.f};
;                 __builtin_amdgcn_sched_barrier(0);
; #pragma unroll
;                 for (int ds = 0; ds < 2; ++ds)
; #pragma unroll
;                     for (int rt = 0; rt < 4; ++rt) va[rt] = MFMA16(fa[2 * rt + ds], sb[ds], va[rt]);
;                 __builtin_amdgcn_sched_barrier(0);
; #pragma unroll
;                 for (int t = 0; t < 8; ++t) fa[t] = *(const bf16x8*)(L + 32768 + ((t * 2 + 0) * 64 + lane) * 16);
;                 __builtin_amdgcn_sched_barrier(0);
; #pragma unroll
;                 for (int ds = 0; ds < 2; ++ds)
; #pragma unroll
;                     for (int rt = 0; rt < 4; ++rt) va[rt] = MFMA16(fb[2 * rt + ds], sb[2 + ds], va[rt]);
;                 __builtin_amdgcn_sched_barrier(0);
; #pragma unroll
;                 for (int t = 0; t < 8; ++t) fb[t] = *(const bf16x8*)(L + 32768 + ((t * 2 + 1) * 64 + lane) * 16);
;                 bf16x8 vb[2];
;                 { u32x2 vn[4];
; #pragma unroll
;                   for (int rt = 0; rt < 4; ++rt) { const u32x2 uu = *(const u32x2*)(L + 57344 + (rt * 64 + lane) * 8);
;                       vn[rt].x = cvt_pk_bf16(bflo(uu.x) - va[rt][0], bfhi(uu.x) - va[rt][1]); vn[rt].y = cvt_pk_bf16(bflo(uu.y) - va[rt][2], bfhi(uu.y) - va[rt][3]); }
; #pragma unroll
;                   for (int s = 0; s < 2; ++s) { u32x4 w; w.x = vn[2 * s].x; w.y = vn[2 * s].y; w.z = vn[2 * s + 1].x; w.w = vn[2 * s + 1].y; vb[s] = __builtin_bit_cast(bf16x8, w);
;                       XV[((st & 1) * 2 + s) * 64 + lane] = vb[s]; } }
; #pragma unroll
.LBB0_680:
	s_add_i32 s16, s16, 1
	s_add_i32 s5, s5, 4
	s_addk_i32 s4, 0x100
	s_cmpk_eq_i32 s16, 0x81
	s_waitcnt lgkmcnt(0)
	s_barrier
	s_cbranch_scc1 .LBB0_683
